# phase A: row rsqrt factors computed in tile prologue under stage-0 load latency; pure gate tiles skip both post-loop block barriers
# baseline (speedup 1.0000x reference)
; DI int tidx() { int t = __builtin_amdgcn_workitem_id_x(); asm volatile("" : "+v"(t)); return t; }
; DI void gemm_tile(const bf16_t* __restrict__ A, int lda, const bf16_t* __restrict__ Bt, int ldb, int bvalid, int K, f32x4 (&acc)[4][4], char* lds, bool preloaded = false) {
;     ...
;   const bf16_t* ap = A + (size_t)lr * lda + ((lc ^ ((lr >> 1) & 7)) << 3);
;   const bf16_t* bp = Bt + ((lc ^ ((lr >> 1) & 7)) << 3);
;   typedef __attribute__((address_space(1))) const unsigned gptr_t;
;   typedef __attribute__((address_space(3))) unsigned lptr_t;
;   const unsigned lbase = (unsigned)(size_t)lds + (unsigned)tid * 16u;
; DI void phaseA_tile(const P& p, int layer, int mt, int nt, char* lds) {
;   const int tid = tidx(), lane = tid & 63, wave = __builtin_amdgcn_readfirstlane(tid >> 6);
;   const int row0 = mt * 128, col0 = nt * 128;
;   const int bvalid = (NP - col0) < 128 ? 64 : 128;
;   float* rr = (float*)(lds + RR_OFF);
;   __syncthreads();
;   const float* sp = (const float*)(p.ws + W_SS) + (size_t)(row0 + (tid & 127)) * 16;
;   const f32x4 ssa = *(const f32x4*)sp, ssb = *(const f32x4*)(sp + 4), ssc = *(const f32x4*)(sp + 8), ssd = *(const f32x4*)(sp + 12);
;   f32x4 acc[4][4];
;   zero_acc(acc);
;   gemm_tile((const bf16_t*)(p.ws + W_XB) + (size_t)row0 * DM, DM, (const bf16_t*)(p.ws + W_WIN) + ((size_t)layer * NP + col0) * 1024, 1024, bvalid, 1024, acc, lds);
;   const int wm = wave >> 1, wn = wave & 1;
;   const int seg = (col0 >> 6) + wn;
;   const int fr = lane & 15, fq = lane >> 4;
;   if (tid < 128) {
;     const float ss = (ssa.x + ssa.y + ssa.z + ssa.w) + (ssb.x + ssb.y + ssb.z + ssb.w) + (ssc.x + ssc.y + ssc.z + ssc.w) + (ssd.x + ssd.y + ssd.z + ssd.w);
;     rr[tid] = rsqrtf(ss * (1.f / 1024.f) + 1e-6f);
;   }
.LBB0_1192:
	s_lshl_b32 s10, s36, 7
	s_ashr_i32 s11, s10, 31
	v_mov_b32_e32 v92, v158
	s_lshl_b32 s0, s37, 7
	s_lshl_b64 s[4:5], s[10:11], 11
	s_add_u32 s12, s74, s4
	v_and_b32_e32 v0, 0x7f, v92
	s_addc_u32 s13, s75, s5
	s_ashr_i32 s1, s0, 31
	v_or_b32_e32 v2, s10, v0
	s_add_u32 s14, s31, s0
	v_ashrrev_i32_e32 v3, 31, v2
	s_addc_u32 s15, s30, s1
	v_lshlrev_b64 v[2:3], 6, v[2:3]
	s_lshl_b64 s[14:15], s[14:15], 11
	v_lshl_add_u64 v[2:3], s[66:67], 0, v[2:3]
	v_mov_b32_e32 v16, v158
	s_add_u32 s14, s90, s14
	s_waitcnt vmcnt(63) expcnt(7) lgkmcnt(15)
	s_barrier
	global_load_dwordx4 v[66:69], v[2:3], off offset:48
	global_load_dwordx4 v[70:73], v[2:3], off offset:32
	global_load_dwordx4 v[74:77], v[2:3], off offset:16
	global_load_dwordx4 v[78:81], v[2:3], off
	s_addc_u32 s15, s91, s15
	v_ashrrev_i32_e32 v2, 3, v16
	v_lshrrev_b32_e32 v17, 4, v16
	v_ashrrev_i32_e32 v3, 31, v2
	v_xor_b32_e32 v0, v17, v16
	s_cmp_gt_i32 s37, 41
	v_lshlrev_b64 v[4:5], 11, v[2:3]
	v_lshlrev_b32_e32 v0, 4, v0
	v_lshl_add_u64 v[6:7], s[12:13], 0, v[4:5]
	v_and_b32_e32 v0, 0x70, v0
	v_lshlrev_b32_e32 v93, 4, v16
	s_cselect_b32 s12, 63, 0x7f
	v_lshl_add_u64 v[6:7], v[6:7], 0, v[0:1]
	v_lshl_add_u64 v[8:9], s[14:15], 0, v[0:1]
	v_add_u32_e32 v3, 0x4000, v93
	v_readfirstlane_b32 s13, v93
	v_and_b32_e32 v0, s12, v2
	s_mov_b32 m0, s13
	v_lshlrev_b32_e32 v0, 11, v0
	v_readfirstlane_b32 s13, v3
	v_add_u32_e32 v3, 0x1000, v93
	global_load_lds_dwordx4 v[6:7], off
	v_lshl_add_u64 v[10:11], v[8:9], 0, v[0:1]
	s_mov_b32 m0, s13
	s_mov_b64 s[14:15], 0x10000
	v_readfirstlane_b32 s13, v3
	v_add_u32_e32 v3, 32, v2
	global_load_lds_dwordx4 v[10:11], off
	v_lshl_add_u64 v[10:11], v[6:7], 0, s[14:15]
	s_mov_b32 m0, s13
	v_and_b32_e32 v3, s12, v3
	global_load_lds_dwordx4 v[10:11], off
	v_lshlrev_b32_e32 v10, 11, v3
	v_add_u32_e32 v3, 0x5000, v93
	v_mov_b32_e32 v11, v1
	v_readfirstlane_b32 s13, v3
	v_add_u32_e32 v3, 0x2000, v93
	v_lshl_add_u64 v[12:13], v[8:9], 0, v[10:11]
	s_mov_b32 m0, s13
	v_readfirstlane_b32 s13, v3
	global_load_lds_dwordx4 v[12:13], off
	v_lshl_add_u64 v[12:13], v[6:7], 0, s[60:61]
	s_mov_b32 m0, s13
	v_bitop3_b32 v3, v2, s12, 64 bitop3:0x48
	global_load_lds_dwordx4 v[12:13], off
	v_lshlrev_b32_e32 v12, 11, v3
	v_add_u32_e32 v3, 0x6000, v93
	v_mov_b32_e32 v13, v1
	v_readfirstlane_b32 s13, v3
	v_add_u32_e32 v3, 0x3000, v93
	v_add_u32_e32 v2, 0x60, v2
	v_lshl_add_u64 v[14:15], v[8:9], 0, v[12:13]
	s_mov_b32 m0, s13
	s_mov_b64 s[14:15], 0x30000
	v_readfirstlane_b32 s13, v3
	v_and_b32_e32 v2, s12, v2
	global_load_lds_dwordx4 v[14:15], off
	v_lshl_add_u64 v[6:7], v[6:7], 0, s[14:15]
	s_mov_b32 m0, s13
	v_lshlrev_b32_e32 v2, 11, v2
	v_mov_b32_e32 v3, v1
	global_load_lds_dwordx4 v[6:7], off
	v_lshl_add_u64 v[6:7], v[8:9], 0, v[2:3]
	v_add_u32_e32 v3, 0x7000, v93
	v_readfirstlane_b32 s11, v16
	v_readfirstlane_b32 s12, v3
	s_mov_b32 m0, s12
	s_lshl_b32 s12, s11, 7
	global_load_lds_dwordx4 v[6:7], off
	v_lshlrev_b32_e32 v3, 7, v16
	s_lshl_b32 s11, s11, 6
	v_bfe_u32 v18, v16, 4, 2
	v_bfe_u32 v20, v16, 1, 3
	s_and_b32 s12, s12, 0x2000
	v_and_b32_e32 v3, 0x780, v3
	s_and_b32 s11, s11, 0xffffe000
	v_or_b32_e32 v94, s12, v3
	v_or_b32_e32 v96, s11, v3
	v_bitop3_b32 v3, v18, v20, 4 bitop3:0x36
	v_lshlrev_b32_e32 v95, 4, v3
	v_bitop3_b32 v3, v17, 7, v16 bitop3:0x48
	v_lshlrev_b32_e32 v3, 4, v3
	v_or_b32_e32 v82, v4, v3
	s_lshl_b64 s[0:1], s[0:1], 11
	s_add_u32 s12, s74, s4
	s_addc_u32 s13, s75, s5
	v_readfirstlane_b32 s33, v93
	s_add_u32 s12, s12, 0x80
	s_addc_u32 s13, s13, 0
	v_add_u32_e32 v83, 0x10000, v82
	v_add_u32_e32 v84, 0x20000, v82
	v_add_u32_e32 v85, 0x30000, v82
	s_add_u32 s14, s2, s0
	s_addc_u32 s15, s3, s1
	v_or_b32_e32 v86, v0, v3
	v_or_b32_e32 v87, v10, v3
	v_lshrrev_b32_e32 v19, 1, v16
	v_or_b32_e32 v88, v12, v3
	v_bitop3_b32 v6, v19, v18, 7 bitop3:0x6c
	v_or_b32_e32 v89, v2, v3
	v_mov_b32_e32 v2, 0
	v_lshlrev_b32_e32 v97, 4, v6
	s_mov_b64 s[0:1], 0
	s_mov_b32 s4, 0
	v_mov_b32_e32 v3, 0
	v_mov_b64_e32 v[4:5], v[2:3]
	v_mov_b64_e32 v[6:7], v[2:3]
	v_mov_b64_e32 v[8:9], v[2:3]
	v_mov_b64_e32 v[10:11], v[2:3]
	v_mov_b64_e32 v[12:13], v[2:3]
	v_mov_b64_e32 v[14:15], v[2:3]
	v_mov_b64_e32 v[16:17], v[2:3]
	v_mov_b64_e32 v[18:19], v[2:3]
	v_mov_b64_e32 v[20:21], v[2:3]
	v_mov_b64_e32 v[22:23], v[2:3]
	v_mov_b64_e32 v[24:25], v[2:3]
	v_mov_b64_e32 v[26:27], v[2:3]
	v_mov_b64_e32 v[28:29], v[2:3]
	v_mov_b64_e32 v[30:31], v[2:3]
	v_mov_b64_e32 v[32:33], v[2:3]
	v_mov_b64_e32 v[34:35], v[2:3]
	v_mov_b64_e32 v[36:37], v[2:3]
	v_mov_b64_e32 v[38:39], v[2:3]
	v_mov_b64_e32 v[40:41], v[2:3]
	v_mov_b64_e32 v[42:43], v[2:3]
	v_mov_b64_e32 v[44:45], v[2:3]
	v_mov_b64_e32 v[46:47], v[2:3]
	v_mov_b64_e32 v[48:49], v[2:3]
	v_mov_b64_e32 v[50:51], v[2:3]
	v_mov_b64_e32 v[52:53], v[2:3]
	v_mov_b64_e32 v[54:55], v[2:3]
	v_mov_b64_e32 v[56:57], v[2:3]
	v_mov_b64_e32 v[58:59], v[2:3]
	v_mov_b64_e32 v[60:61], v[2:3]
	v_mov_b64_e32 v[62:63], v[2:3]
	v_mov_b64_e32 v[64:65], v[2:3]
	s_waitcnt vmcnt(8)
	v_cmp_gt_i32_e32 vcc, 0x80, v92
	s_and_saveexec_b64 s[98:99], vcc
	v_mov_b32_e32 v98, v78
	v_mov_b32_e32 v99, v74
	v_mov_b32_e32 v74, v79
	v_pk_add_f32 v[74:75], v[98:99], v[74:75]
	v_mov_b32_e32 v78, v80
	v_mov_b32_e32 v79, v76
	v_pk_add_f32 v[74:75], v[78:79], v[74:75]
	v_mov_b32_e32 v76, v81
	v_pk_add_f32 v[74:75], v[76:77], v[74:75]
	v_mov_b32_e32 v76, v70
	v_mov_b32_e32 v77, v66
	v_mov_b32_e32 v66, v71
	v_pk_add_f32 v[66:67], v[76:77], v[66:67]
	v_mov_b32_e32 v70, v72
	v_mov_b32_e32 v71, v68
	v_pk_add_f32 v[66:67], v[70:71], v[66:67]
	v_mov_b32_e32 v68, v73
	v_pk_add_f32 v[66:67], v[68:69], v[66:67]
	v_add_f32_e32 v0, v74, v75
	v_add_f32_e32 v0, v0, v66
	v_add_f32_e32 v0, v0, v67
	v_fmamk_f32 v0, v0, 0x3a800000, v160
	s_mov_b32 s5, 0x800000
	v_mul_f32_e32 v66, 0x4b800000, v0
	v_cmp_gt_f32_e32 vcc, s5, v0
	s_nop 1
	v_cndmask_b32_e32 v0, v0, v66, vcc
	v_rsq_f32_e32 v0, v0
	s_nop 0
	v_mul_f32_e32 v66, 0x45800000, v0
	v_cndmask_b32_e32 v0, v0, v66, vcc
	v_lshl_add_u32 v66, v92, 2, v173
	ds_write_b32 v66, v0
	s_or_b64 exec, exec, s[98:99]
	s_waitcnt vmcnt(0) lgkmcnt(0)
	s_barrier
	.p2alignl 6, 3212836864
; #define MFMA16(a, b, c) __builtin_amdgcn_mfma_f32_16x16x32_bf16((a), (b), (c), 0, 0, 0)
; DI void gemm_tile(const bf16_t* __restrict__ A, int lda, const bf16_t* __restrict__ Bt, int ldb, int bvalid, int K, f32x4 (&acc)[4][4], char* lds, bool preloaded = false) {
;     ...
;   auto compute = [&](int st) {
;     const char* base = lds + st * 32768;
;     bf16x8 af[2][4], bfr[2][4];
; #pragma unroll
;     for (int s = 0; s < 2; ++s) {
;       const int ch = ((4 * s + fq) ^ fx) << 4;
; #pragma unroll
;       for (int mi = 0; mi < 4; ++mi) af[s][mi] = *(const bf16x8*)(base + (wm * 64 + mi * 16 + fr) * 128 + ch);
; #pragma unroll
;       for (int ni = 0; ni < 4; ++ni) bfr[s][ni] = *(const bf16x8*)(base + 16384 + (wn * 64 + ni * 16 + fr) * 128 + ch);
;     }
;     __builtin_amdgcn_s_setprio(1);
; #pragma unroll
;     for (int s = 0; s < 2; ++s)
; #pragma unroll
;       for (int mi = 0; mi < 4; ++mi)
; #pragma unroll
;         for (int ni = 0; ni < 4; ++ni) acc[mi][ni] = MFMA16(af[s][mi], bfr[s][ni], acc[mi][ni]);
;     __builtin_amdgcn_s_setprio(0);
;   };
;   const int nk = K >> 6;
;   if (!preloaded) { GLDS(0, 0) }
;   __syncthreads();
;   for (int kt = 0; kt < nk; ++kt) {
;     if (kt + 1 < nk) { GLDS((kt + 1) & 1, (kt + 1) << 6) }
;     compute(kt & 1);
;     __syncthreads();
.LBB0_1193:
	s_add_i32 s5, s4, 0x8000
	s_and_b32 s11, s5, 0x8000
	s_and_b32 s4, s4, 0x8000
	v_or_b32_e32 v0, s4, v97
	v_add_u32_e32 v110, v0, v96
	v_add_u32_e32 v0, v0, v94
	ds_read_b128 v[98:101], v110
	ds_read_b128 v[114:117], v0 offset:16384
	ds_read_b128 v[118:121], v0 offset:18432
	ds_read_b128 v[122:125], v0 offset:20480
	ds_read_b128 v[126:129], v0 offset:22528
	ds_read_b128 v[102:105], v110 offset:2048
	ds_read_b128 v[106:109], v110 offset:4096
	ds_read_b128 v[110:113], v110 offset:6144
	s_add_i32 m0, s33, s11
	v_or_b32_e32 v0, s4, v95
	global_load_lds_dwordx4 v82, s[12:13]
	s_addk_i32 m0, 0x1000
	v_add_u32_e32 v142, v0, v96
	global_load_lds_dwordx4 v83, s[12:13]
	s_addk_i32 m0, 0x1000
	v_add_u32_e32 v0, v0, v94
	global_load_lds_dwordx4 v84, s[12:13]
	s_addk_i32 m0, 0x1000
	ds_read_b128 v[130:133], v142
	global_load_lds_dwordx4 v85, s[12:13]
	s_addk_i32 m0, 0x1000
	ds_read_b128 v[146:149], v0 offset:16384
	global_load_lds_dwordx4 v86, s[14:15]
	s_addk_i32 m0, 0x1000
	ds_read_b128 v[150:153], v0 offset:18432
	global_load_lds_dwordx4 v87, s[14:15]
	s_addk_i32 m0, 0x1000
	ds_read_b128 v[154:157], v0 offset:20480
	global_load_lds_dwordx4 v88, s[14:15]
	s_addk_i32 m0, 0x1000
	ds_read_b128 v[180:183], v0 offset:22528
	global_load_lds_dwordx4 v89, s[14:15]
	ds_read_b128 v[134:137], v142 offset:2048
	ds_read_b128 v[138:141], v142 offset:4096
	ds_read_b128 v[142:145], v142 offset:6144
	s_add_u32 s12, s12, 0x80
	s_addc_u32 s13, s13, 0
	s_add_u32 s14, s14, 0x80
	s_addc_u32 s15, s15, 0
	s_setprio 1
	s_waitcnt lgkmcnt(11)
	v_mfma_f32_16x16x32_bf16 v[62:65], v[98:101], v[114:117], v[62:65]
	v_mfma_f32_16x16x32_bf16 v[58:61], v[98:101], v[118:121], v[58:61]
	v_mfma_f32_16x16x32_bf16 v[54:57], v[98:101], v[122:125], v[54:57]
	v_mfma_f32_16x16x32_bf16 v[50:53], v[98:101], v[126:129], v[50:53]
	s_waitcnt lgkmcnt(8)
	v_mfma_f32_16x16x32_bf16 v[46:49], v[102:105], v[114:117], v[46:49]
	v_mfma_f32_16x16x32_bf16 v[42:45], v[102:105], v[118:121], v[42:45]
	v_mfma_f32_16x16x32_bf16 v[38:41], v[102:105], v[122:125], v[38:41]
	v_mfma_f32_16x16x32_bf16 v[34:37], v[102:105], v[126:129], v[34:37]
	v_mfma_f32_16x16x32_bf16 v[30:33], v[106:109], v[114:117], v[30:33]
	v_mfma_f32_16x16x32_bf16 v[26:29], v[106:109], v[118:121], v[26:29]
	v_mfma_f32_16x16x32_bf16 v[22:25], v[106:109], v[122:125], v[22:25]
	v_mfma_f32_16x16x32_bf16 v[18:21], v[106:109], v[126:129], v[18:21]
	v_mfma_f32_16x16x32_bf16 v[14:17], v[110:113], v[114:117], v[14:17]
	v_mfma_f32_16x16x32_bf16 v[10:13], v[110:113], v[118:121], v[10:13]
	v_mfma_f32_16x16x32_bf16 v[6:9], v[110:113], v[122:125], v[6:9]
	v_mfma_f32_16x16x32_bf16 v[2:5], v[110:113], v[126:129], v[2:5]
	s_waitcnt lgkmcnt(3)
	v_mfma_f32_16x16x32_bf16 v[62:65], v[130:133], v[146:149], v[62:65]
	v_mfma_f32_16x16x32_bf16 v[58:61], v[130:133], v[150:153], v[58:61]
	v_mfma_f32_16x16x32_bf16 v[54:57], v[130:133], v[154:157], v[54:57]
	v_mfma_f32_16x16x32_bf16 v[50:53], v[130:133], v[180:183], v[50:53]
	s_waitcnt lgkmcnt(0)
	v_mfma_f32_16x16x32_bf16 v[46:49], v[134:137], v[146:149], v[46:49]
	v_mfma_f32_16x16x32_bf16 v[42:45], v[134:137], v[150:153], v[42:45]
	v_mfma_f32_16x16x32_bf16 v[38:41], v[134:137], v[154:157], v[38:41]
	v_mfma_f32_16x16x32_bf16 v[34:37], v[134:137], v[180:183], v[34:37]
	v_mfma_f32_16x16x32_bf16 v[30:33], v[138:141], v[146:149], v[30:33]
	v_mfma_f32_16x16x32_bf16 v[26:29], v[138:141], v[150:153], v[26:29]
	v_mfma_f32_16x16x32_bf16 v[22:25], v[138:141], v[154:157], v[22:25]
	v_mfma_f32_16x16x32_bf16 v[18:21], v[138:141], v[180:183], v[18:21]
	v_mfma_f32_16x16x32_bf16 v[14:17], v[142:145], v[146:149], v[14:17]
	v_mfma_f32_16x16x32_bf16 v[10:13], v[142:145], v[150:153], v[10:13]
	v_mfma_f32_16x16x32_bf16 v[6:9], v[142:145], v[154:157], v[6:9]
	v_mfma_f32_16x16x32_bf16 v[2:5], v[142:145], v[180:183], v[2:5]
	s_setprio 0
	s_add_u32 s0, s0, 0x80
	s_cmpk_eq_i32 s0, 0x780
	s_mov_b32 s4, s5
	s_waitcnt vmcnt(0)
	s_barrier
	s_cbranch_scc0 .LBB0_1193
; #define MFMA16(a, b, c) __builtin_amdgcn_mfma_f32_16x16x32_bf16((a), (b), (c), 0, 0, 0)
; DI void gemm_tile(const bf16_t* __restrict__ A, int lda, const bf16_t* __restrict__ Bt, int ldb, int bvalid, int K, f32x4 (&acc)[4][4], char* lds, bool preloaded = false) {
;     ...
;   auto compute = [&](int st) {
;     const char* base = lds + st * 32768;
;     bf16x8 af[2][4], bfr[2][4];
; #pragma unroll
;     for (int s = 0; s < 2; ++s) {
;       const int ch = ((4 * s + fq) ^ fx) << 4;
; #pragma unroll
;       for (int mi = 0; mi < 4; ++mi) af[s][mi] = *(const bf16x8*)(base + (wm * 64 + mi * 16 + fr) * 128 + ch);
; #pragma unroll
;       for (int ni = 0; ni < 4; ++ni) bfr[s][ni] = *(const bf16x8*)(base + 16384 + (wn * 64 + ni * 16 + fr) * 128 + ch);
;     }
;     __builtin_amdgcn_s_setprio(1);
; #pragma unroll
;     for (int s = 0; s < 2; ++s)
; #pragma unroll
;       for (int mi = 0; mi < 4; ++mi)
; #pragma unroll
;         for (int ni = 0; ni < 4; ++ni) acc[mi][ni] = MFMA16(af[s][mi], bfr[s][ni], acc[mi][ni]);
;     __builtin_amdgcn_s_setprio(0);
;   };
;   const int nk = K >> 6;
;   if (!preloaded) { GLDS(0, 0) }
;   __syncthreads();
;   for (int kt = 0; kt < nk; ++kt) {
;     if (kt + 1 < nk) { GLDS((kt + 1) & 1, (kt + 1) << 6) }
;     compute(kt & 1);
;     __syncthreads();
; DI void phaseA_tile(const P& p, int layer, int mt, int nt, char* lds) {
;     ...
;   const int wm = wave >> 1, wn = wave & 1;
;   const int seg = (col0 >> 6) + wn;
;   const int fr = lane & 15, fq = lane >> 4;
;   if (tid < 128) {
;     const float ss = (ssa.x + ssa.y + ssa.z + ssa.w) + (ssb.x + ssb.y + ssb.z + ssb.w) + (ssc.x + ssc.y + ssc.z + ssc.w) + (ssd.x + ssd.y + ssd.z + ssd.w);
;     rr[tid] = rsqrtf(ss * (1.f / 1024.f) + 1e-6f);
;   }
;   float* stg = (float*)lds;
;   stage_acc(acc, stg, wm, wn, fr, fq);
;   __syncthreads();
;   if (seg >= NSEG) return;
	v_add_u32_e32 v0, v97, v96
	ds_read_b128 v[82:85], v0 offset:32768
	ds_read_b128 v[86:89], v0 offset:34816
	ds_read_b128 v[98:101], v0 offset:36864
	ds_read_b128 v[102:105], v0 offset:38912
	v_add_u32_e32 v0, v97, v94
	ds_read_b128 v[106:109], v0 offset:49152
	ds_read_b128 v[110:113], v0 offset:51200
	ds_read_b128 v[114:117], v0 offset:53248
	ds_read_b128 v[118:121], v0 offset:55296
	v_add_u32_e32 v0, v95, v96
	ds_read_b128 v[122:125], v0 offset:32768
	ds_read_b128 v[126:129], v0 offset:34816
	ds_read_b128 v[130:133], v0 offset:36864
	ds_read_b128 v[134:137], v0 offset:38912
	v_add_u32_e32 v0, v95, v94
	ds_read_b128 v[94:97], v0 offset:49152
	ds_read_b128 v[138:141], v0 offset:51200
	ds_read_b128 v[142:145], v0 offset:53248
	ds_read_b128 v[146:149], v0 offset:55296
	s_movk_i32 s33, 0x210
	v_readfirstlane_b32 s4, v92
	s_setprio 1
	s_waitcnt lgkmcnt(11)
	v_mfma_f32_16x16x32_bf16 v[62:65], v[82:85], v[106:109], v[62:65]
	s_waitcnt lgkmcnt(10)
	v_mfma_f32_16x16x32_bf16 v[58:61], v[82:85], v[110:113], v[58:61]
	s_waitcnt lgkmcnt(9)
	v_mfma_f32_16x16x32_bf16 v[54:57], v[82:85], v[114:117], v[54:57]
	s_waitcnt lgkmcnt(8)
	v_mfma_f32_16x16x32_bf16 v[50:53], v[82:85], v[118:121], v[50:53]
	v_mfma_f32_16x16x32_bf16 v[46:49], v[86:89], v[106:109], v[46:49]
	v_mfma_f32_16x16x32_bf16 v[42:45], v[86:89], v[110:113], v[42:45]
	v_mfma_f32_16x16x32_bf16 v[38:41], v[86:89], v[114:117], v[38:41]
	v_mfma_f32_16x16x32_bf16 v[34:37], v[86:89], v[118:121], v[34:37]
	v_mfma_f32_16x16x32_bf16 v[30:33], v[98:101], v[106:109], v[30:33]
	v_mfma_f32_16x16x32_bf16 v[26:29], v[98:101], v[110:113], v[26:29]
	v_mfma_f32_16x16x32_bf16 v[22:25], v[98:101], v[114:117], v[22:25]
	v_mfma_f32_16x16x32_bf16 v[18:21], v[98:101], v[118:121], v[18:21]
	v_mfma_f32_16x16x32_bf16 v[14:17], v[102:105], v[106:109], v[14:17]
	v_mfma_f32_16x16x32_bf16 v[10:13], v[102:105], v[110:113], v[10:13]
	v_mfma_f32_16x16x32_bf16 v[6:9], v[102:105], v[114:117], v[6:9]
	v_mfma_f32_16x16x32_bf16 v[2:5], v[102:105], v[118:121], v[2:5]
	s_waitcnt lgkmcnt(3)
	v_mfma_f32_16x16x32_bf16 v[62:65], v[122:125], v[94:97], v[62:65]
	s_waitcnt lgkmcnt(2)
	v_mfma_f32_16x16x32_bf16 v[58:61], v[122:125], v[138:141], v[58:61]
	s_waitcnt lgkmcnt(1)
	v_mfma_f32_16x16x32_bf16 v[54:57], v[122:125], v[142:145], v[54:57]
	s_waitcnt lgkmcnt(0)
	v_mfma_f32_16x16x32_bf16 v[50:53], v[122:125], v[146:149], v[50:53]
	v_mfma_f32_16x16x32_bf16 v[46:49], v[126:129], v[94:97], v[46:49]
	v_mfma_f32_16x16x32_bf16 v[42:45], v[126:129], v[138:141], v[42:45]
	v_mfma_f32_16x16x32_bf16 v[38:41], v[126:129], v[142:145], v[38:41]
	v_mfma_f32_16x16x32_bf16 v[34:37], v[126:129], v[146:149], v[34:37]
	v_mfma_f32_16x16x32_bf16 v[30:33], v[130:133], v[94:97], v[30:33]
	v_mfma_f32_16x16x32_bf16 v[26:29], v[130:133], v[138:141], v[26:29]
	v_mfma_f32_16x16x32_bf16 v[22:25], v[130:133], v[142:145], v[22:25]
	v_mfma_f32_16x16x32_bf16 v[18:21], v[130:133], v[146:149], v[18:21]
	v_mfma_f32_16x16x32_bf16 v[14:17], v[134:137], v[94:97], v[14:17]
	v_mfma_f32_16x16x32_bf16 v[10:13], v[134:137], v[138:141], v[10:13]
	v_mfma_f32_16x16x32_bf16 v[6:9], v[134:137], v[142:145], v[6:9]
	v_mfma_f32_16x16x32_bf16 v[2:5], v[134:137], v[146:149], v[2:5]
	s_setprio 0
	s_cmp_gt_i32 s37, 26
	s_cbranch_scc1 .Lnob1_a1
	s_barrier
.Lnob1_a1:
	s_ashr_i32 s56, s4, 7
	s_bfe_u32 s0, s4, 0x10006
	v_bfe_u32 v88, v92, 4, 2
	v_and_b32_e32 v89, 15, v92
	s_lshl_b32 s11, s56, 6
	v_lshlrev_b32_e32 v127, 2, v88
	s_lshl_b32 s57, s0, 8
	s_lshl_b32 s20, s37, 1
	v_or_b32_e32 v66, s11, v127
	v_lshl_or_b32 v0, v89, 2, s57
	s_or_b32 s55, s0, s20
	v_mad_u64_u32 v[66:67], s[0:1], v66, s33, v[0:1]
	s_cmp_gt_i32 s55, 52
	s_cbranch_scc1 .Lstg_skip_a1
	v_add_u32_e32 v0, 0x400, v66
	ds_write2_b32 v66, v62, v58 offset1:16
	ds_write2_b32 v66, v63, v59 offset0:132 offset1:148
	ds_write2_b32 v0, v64, v60 offset0:8 offset1:24
	ds_write2_b32 v0, v65, v61 offset0:140 offset1:156
	ds_write2_b32 v66, v54, v50 offset0:32 offset1:48
	ds_write2_b32 v66, v55, v51 offset0:164 offset1:180
	ds_write2_b32 v0, v56, v52 offset0:40 offset1:56
	ds_write2_b32 v0, v57, v53 offset0:172 offset1:188
	v_add_u32_e32 v0, 0x2000, v66
	v_add_u32_e32 v67, 0x2400, v66
	ds_write2_b32 v0, v46, v42 offset0:64 offset1:80
	ds_write2_b32 v0, v47, v43 offset0:196 offset1:212
	ds_write2_b32 v67, v48, v44 offset0:72 offset1:88
	ds_write2_b32 v67, v49, v45 offset0:204 offset1:220
	ds_write2_b32 v0, v38, v34 offset0:96 offset1:112
	ds_write2_b32 v0, v39, v35 offset0:228 offset1:244
	ds_write2_b32 v67, v40, v36 offset0:104 offset1:120
	ds_write2_b32 v67, v41, v37 offset0:236 offset1:252
	v_add_u32_e32 v0, 0x4000, v66
	v_add_u32_e32 v67, 0x4400, v66
	v_add_u32_e32 v68, 0x4800, v66
	ds_write2_b32 v0, v30, v26 offset0:128 offset1:144
	ds_write2_b32 v67, v31, v27 offset0:4 offset1:20
	ds_write2_b32 v67, v32, v28 offset0:136 offset1:152
	ds_write2_b32 v68, v33, v29 offset0:12 offset1:28
	ds_write2_b32 v0, v22, v18 offset0:160 offset1:176
	ds_write2_b32 v67, v23, v19 offset0:36 offset1:52
	ds_write2_b32 v67, v24, v20 offset0:168 offset1:184
	ds_write2_b32 v68, v25, v21 offset0:44 offset1:60
	v_add_u32_e32 v0, 0x6000, v66
	v_add_u32_e32 v67, 0x6400, v66
	v_add_u32_e32 v66, 0x6800, v66
	ds_write2_b32 v0, v14, v10 offset0:192 offset1:208
	ds_write2_b32 v67, v15, v11 offset0:68 offset1:84
	ds_write2_b32 v67, v16, v12 offset0:200 offset1:216
	ds_write2_b32 v66, v17, v13 offset0:76 offset1:92
	ds_write2_b32 v0, v6, v2 offset0:224 offset1:240
	ds_write2_b32 v67, v7, v3 offset0:100 offset1:116
	ds_write2_b32 v67, v8, v4 offset0:232 offset1:248
	ds_write2_b32 v66, v9, v5 offset0:108 offset1:124
.Lstg_skip_a1:
	s_cmp_gt_i32 s37, 26
	s_cbranch_scc1 .Lnob2_a1
	s_waitcnt lgkmcnt(0)
	s_barrier
.Lnob2_a1:
	s_cmpk_gt_i32 s55, 0x54
	s_movk_i32 s5, 0x2000
	s_cbranch_scc1 .LBB0_1183
	v_and_b32_e32 v152, 63, v92
	s_cmp_lt_i32 s55, 53
	s_mov_b64 s[0:1], -1
	s_cbranch_scc0 .LBB0_1584
	s_cmpk_gt_i32 s36, 0xff
	s_cselect_b64 s[38:39], -1, 0
	s_cmpk_lt_i32 s36, 0x100
	s_cselect_b64 s[12:13], -1, 0
	s_and_b32 s0, s37, 0x7ffffffc
	s_cmp_lg_u32 s0, 16
	s_cbranch_scc1 .LBB0_1264
	v_lshlrev_b32_e32 v0, 2, v127
	v_lshl_add_u32 v0, s11, 2, v0
	s_add_i32 s16, s11, s10
	v_add_u32_e32 v80, 0x10800, v0
	s_ashr_i32 s0, s16, 8
	ds_read_b128 v[66:69], v80
	s_sub_i32 s14, s55, 32
	s_and_b32 s0, s0, -8
	s_or_b32 s0, s0, s14
	s_ashr_i32 s1, s0, 31
	s_lshl_b64 s[0:1], s[0:1], 18
	s_mov_b64 s[4:5], -1
	s_and_b64 vcc, exec, s[12:13]
	v_lshlrev_b32_e32 v70, 12, v89
	s_cbranch_vccz .LBB0_1201
	v_readlane_b32 s4, v240, 52
	s_add_u32 s4, s4, s0
	v_readlane_b32 s5, v240, 53
	s_addc_u32 s5, s5, s1
	v_mov_b32_e32 v71, v1
	v_lshl_add_u64 v[72:73], s[4:5], 0, v[70:71]
	s_mov_b64 s[4:5], 0
